# GEMM: first K-iteration peeled with srcC=0 (no per-tile accumulator zeroing); row_rstd rsqrt without dead denormal path
# baseline (speedup 1.0000x reference)
; DI float row_rstd(const float* SS, int row) { return rsqrtf(SS[row] * (1.0f / 1024.0f) + 1e-6f); }
;     DI void operator()(const Acc& acc, const pg8::Unit& u, int wr, int wc, int fr, int fq) const {
;         const int row0 = u.pm * 256 + wr * 64 + fr, cl = wc * 32 + fq * 8;
;         float rsv[2][4];
; #pragma unroll
;         for (int ai = 0; ai < 2; ++ai)
; #pragma unroll
;             for (int m = 0; m < 4; ++m) rsv[ai][m] = row_rstd(SS, row0 + ai * 128 + m * 16);
;         if (u.pn < 8) {
.LBB0_296:
	v_lshl_add_u32 v154, s78, 8, v188
	v_ashrrev_i32_e32 v155, 31, v154
	v_lshl_add_u64 v[148:149], v[154:155], 2, s[6:7]
	global_load_dword v234, v[148:149], off
	v_or_b32_e32 v158, 16, v154
	v_ashrrev_i32_e32 v159, 31, v158
	v_or_b32_e32 v162, 32, v154
	v_ashrrev_i32_e32 v163, 31, v162
	v_or_b32_e32 v166, 48, v154
	v_ashrrev_i32_e32 v167, 31, v166
	v_add_u32_e32 v182, 0x80, v154
	v_add_u32_e32 v196, 0x90, v154
	v_add_u32_e32 v198, 0xa0, v154
	v_add_u32_e32 v180, 0xb0, v154
	v_ashrrev_i32_e32 v183, 31, v182
	v_ashrrev_i32_e32 v197, 31, v196
	v_ashrrev_i32_e32 v199, 31, v198
	v_ashrrev_i32_e32 v181, 31, v180
	s_mov_b64 s[78:79], -1
	s_cmp_gt_i32 s4, 7
	v_lshlrev_b64 v[178:179], 10, v[154:155]
	v_lshlrev_b64 v[176:177], 10, v[158:159]
	v_lshlrev_b64 v[174:175], 10, v[162:163]
	v_lshlrev_b64 v[172:173], 10, v[166:167]
	v_lshlrev_b64 v[154:155], 10, v[198:199]
	v_lshl_add_u64 v[150:151], v[158:159], 2, s[6:7]
	global_load_dword v235, v[150:151], off
	v_lshl_add_u64 v[150:151], v[162:163], 2, s[6:7]
	global_load_dword v236, v[150:151], off
	v_lshl_add_u64 v[150:151], v[166:167], 2, s[6:7]
	global_load_dword v237, v[150:151], off
	global_load_dword v238, v[148:149], off offset:512
	global_load_dword v239, v[148:149], off offset:576
	global_load_dword v240, v[148:149], off offset:640
	global_load_dword v241, v[148:149], off offset:704
	s_waitcnt vmcnt(0)
	v_fmamk_f32 v138, v234, 0x3a800000, v195
	s_nop 0
	v_rsq_f32_e32 v138, v138
	s_nop 0
	v_mov_b32_e32 v170, v138
	v_lshlrev_b64 v[158:159], 10, v[180:181]
	v_fmamk_f32 v138, v235, 0x3a800000, v195
	s_nop 0
	v_rsq_f32_e32 v138, v138
	s_nop 0
	v_mov_b32_e32 v168, v138
	v_lshlrev_b64 v[162:163], 10, v[196:197]
	v_fmamk_f32 v138, v236, 0x3a800000, v195
	s_nop 0
	v_rsq_f32_e32 v138, v138
	s_nop 0
	v_mov_b32_e32 v164, v138
	v_lshlrev_b64 v[166:167], 10, v[182:183]
	v_fmamk_f32 v138, v237, 0x3a800000, v195
	s_nop 0
	v_rsq_f32_e32 v138, v138
	s_nop 0
	v_mov_b32_e32 v160, v138
	v_fmamk_f32 v138, v238, 0x3a800000, v195
	s_nop 0
	v_rsq_f32_e32 v138, v138
	s_nop 0
	v_mov_b32_e32 v156, v138
	v_fmamk_f32 v138, v239, 0x3a800000, v195
	s_nop 0
	v_rsq_f32_e32 v138, v138
	s_nop 0
	v_mov_b32_e32 v152, v138
	v_fmamk_f32 v138, v240, 0x3a800000, v195
	s_nop 0
	v_rsq_f32_e32 v138, v138
	s_nop 0
	v_mov_b32_e32 v150, v138
	v_fmamk_f32 v138, v241, 0x3a800000, v195
	s_nop 0
	v_rsq_f32_e32 v138, v138
	s_nop 0
	v_mov_b32_e32 v148, v138
	s_cbranch_scc1 .LBB0_299
	s_andn2_b64 vcc, exec, s[78:79]
	s_cbranch_vccz .LBB0_300

; DI u32x4 pk8(f32x4 a, f32x4 b) { u32x4 w; w.x = pk2(a[0], a[1]); w.y = pk2(a[2], a[3]); w.z = pk2(b[0], b[1]); w.w = pk2(b[2], b[3]); return w; }
; DI float row_rstd(const float* SS, int row) { return rsqrtf(SS[row] * (1.0f / 1024.0f) + 1e-6f); }
;     DI void operator()(const Acc& acc, const pg8::Unit& u, int wr, int wc, int fr, int fq) const {
;         const int colb = u.pn * 128 + wc * 32 + fq * 8;
;         float rsv[2][4];
; #pragma unroll
;         for (int ai = 0; ai < 2; ++ai)
; #pragma unroll
;             for (int m = 0; m < 4; ++m) rsv[ai][m] = row_rstd(SS, u.pm * 256 + ai * 128 + wr * 64 + m * 16 + fr);
; #pragma unroll
;         for (int ai = 0; ai < 2; ++ai)
; #pragma unroll
;             for (int m = 0; m < 4; ++m) {
;                 const int row = u.pm * 256 + ai * 128 + wr * 64 + m * 16 + fr;
;                 const float rs = rsv[ai][m];
;                 f32x4 h0, h1;
;                 const float rs2 = rs * rs, nrl = -rs * LOG2E;
; #pragma unroll
;                 for (int i = 0; i < 4; ++i) {
;                     const float a0 = acc[ai][0][m][0][i], a1 = acc[ai][0][m][1][i];
;                     h0[i] = (a0 * acc[ai][1][m][0][i]) * rs2 * __builtin_amdgcn_rcpf(1.0f + __builtin_amdgcn_exp2f(a0 * nrl));
;                     h1[i] = (a1 * acc[ai][1][m][1][i]) * rs2 * __builtin_amdgcn_rcpf(1.0f + __builtin_amdgcn_exp2f(a1 * nrl));
;                 }
;                 __builtin_nontemporal_store(pk8(h0, h1), (u32x4*)(HID + (size_t)row * FH + colb));
.LBB0_612:
	v_lshl_add_u32 v160, s4, 8, v165
	v_ashrrev_i32_e32 v161, 31, v160
	v_lshl_add_u64 v[146:147], v[160:161], 2, s[50:51]
	v_or_b32_e32 v158, 16, v160
	global_load_dword v161, v[146:147], off
	v_ashrrev_i32_e32 v159, 31, v158
	v_or_b32_e32 v156, 32, v160
	v_or_b32_e32 v154, 48, v160
	v_add_u32_e32 v152, 0x80, v160
	v_add_u32_e32 v150, 0x90, v160
	v_add_u32_e32 v148, 0xa0, v160
	v_add_u32_e32 v146, 0xb0, v160
	v_lshl_add_u64 v[172:173], v[158:159], 2, s[50:51]
	v_ashrrev_i32_e32 v157, 31, v156
	v_ashrrev_i32_e32 v155, 31, v154
	v_ashrrev_i32_e32 v153, 31, v152
	v_ashrrev_i32_e32 v151, 31, v150
	v_ashrrev_i32_e32 v149, 31, v148
	v_ashrrev_i32_e32 v147, 31, v146
	v_lshl_add_u64 v[174:175], v[156:157], 2, s[50:51]
	v_lshl_add_u64 v[176:177], v[154:155], 2, s[50:51]
	v_lshl_add_u64 v[178:179], v[152:153], 2, s[50:51]
	v_lshl_add_u64 v[180:181], v[150:151], 2, s[50:51]
	v_lshl_add_u64 v[182:183], v[148:149], 2, s[50:51]
	v_lshl_add_u64 v[184:185], v[146:147], 2, s[50:51]
	global_load_dword v147, v[172:173], off
	global_load_dword v149, v[174:175], off
	global_load_dword v151, v[176:177], off
	global_load_dword v153, v[178:179], off
	global_load_dword v155, v[180:181], off
	global_load_dword v157, v[182:183], off
	global_load_dword v159, v[184:185], off
	v_lshl_or_b32 v172, s5, 7, v167
	v_pk_mul_f32 v[122:123], v[126:127], v[122:123]
	v_pk_mul_f32 v[116:117], v[120:121], v[116:117]
	v_pk_mul_f32 v[114:115], v[118:119], v[114:115]
	v_pk_mul_f32 v[124:125], v[128:129], v[124:125]
	v_ashrrev_i32_e32 v173, 31, v172
	v_pk_mul_f32 v[106:107], v[110:111], v[106:107]
	v_pk_mul_f32 v[98:99], v[102:103], v[98:99]
	v_pk_mul_f32 v[100:101], v[104:105], v[100:101]
	v_pk_mul_f32 v[108:109], v[112:113], v[108:109]
	v_pk_mul_f32 v[90:91], v[94:95], v[90:91]
	v_pk_mul_f32 v[82:83], v[86:87], v[82:83]
	v_pk_mul_f32 v[84:85], v[88:89], v[84:85]
	v_pk_mul_f32 v[92:93], v[96:97], v[92:93]
	v_pk_mul_f32 v[74:75], v[78:79], v[74:75]
	v_pk_mul_f32 v[66:67], v[70:71], v[66:67]
	v_pk_mul_f32 v[68:69], v[72:73], v[68:69]
	v_pk_mul_f32 v[76:77], v[80:81], v[76:77]
	v_pk_mul_f32 v[58:59], v[62:63], v[58:59]
	v_pk_mul_f32 v[50:51], v[54:55], v[50:51]
	v_pk_mul_f32 v[52:53], v[56:57], v[52:53]
	v_pk_mul_f32 v[60:61], v[64:65], v[60:61]
	v_pk_mul_f32 v[42:43], v[46:47], v[42:43]
	v_pk_mul_f32 v[34:35], v[38:39], v[34:35]
	v_pk_mul_f32 v[36:37], v[40:41], v[36:37]
	v_pk_mul_f32 v[44:45], v[48:49], v[44:45]
	v_pk_mul_f32 v[26:27], v[30:31], v[26:27]
	v_pk_mul_f32 v[18:19], v[22:23], v[18:19]
	v_pk_mul_f32 v[20:21], v[24:25], v[20:21]
	v_pk_mul_f32 v[28:29], v[32:33], v[28:29]
	v_pk_mul_f32 v[10:11], v[14:15], v[10:11]
	v_pk_mul_f32 v[2:3], v[6:7], v[2:3]
	v_pk_mul_f32 v[4:5], v[8:9], v[4:5]
	v_pk_mul_f32 v[12:13], v[16:17], v[12:13]
	s_waitcnt vmcnt(0)
	v_fmamk_f32 v161, v161, 0x3a800000, v171
	v_fmamk_f32 v147, v147, 0x3a800000, v171
	v_fmamk_f32 v149, v149, 0x3a800000, v171
	v_fmamk_f32 v157, v157, 0x3a800000, v171
	v_fmamk_f32 v159, v159, 0x3a800000, v171
	v_rsq_f32_e32 v161, v161
	v_fmamk_f32 v151, v151, 0x3a800000, v171
	v_rsq_f32_e32 v149, v149
	v_rsq_f32_e32 v157, v157
	v_fmamk_f32 v153, v153, 0x3a800000, v171
	v_rsq_f32_e32 v147, v147
	v_rsq_f32_e32 v159, v159
	v_rsq_f32_e32 v151, v151
	v_rsq_f32_e32 v153, v153
	v_fmamk_f32 v155, v155, 0x3a800000, v171
	v_mov_b32_e32 v175, v149
	v_mov_b32_e32 v149, v157
	v_mul_f32_e32 v157, 0xbfb8aa3b, v161
	v_mov_b32_e32 v181, v147
	v_mov_b32_e32 v147, v159
	v_mul_f32_e32 v159, v126, v157
	v_mul_f32_e32 v174, v161, v161
	v_mul_f32_e32 v161, v118, v157
	v_exp_f32_e32 v159, v159
	v_rsq_f32_e32 v155, v155
	v_mul_f32_e32 v176, v127, v157
	v_exp_f32_e32 v161, v161
	v_exp_f32_e32 v177, v176
	v_add_f32_e32 v159, 1.0, v159
	v_rcp_f32_e32 v176, v159
	v_add_f32_e32 v159, 1.0, v161
	v_rcp_f32_e32 v178, v159
	v_add_f32_e32 v159, 1.0, v177
	v_rcp_f32_e32 v177, v159
	v_mul_f32_e32 v159, v119, v157
	v_exp_f32_e32 v159, v159
	v_mul_f32_e32 v119, v120, v157
	v_mul_f32_e32 v120, v129, v157
	v_mul_f32_e32 v118, v128, v157
	v_add_f32_e32 v126, 1.0, v159
	v_rcp_f32_e32 v179, v126
	v_exp_f32_e32 v119, v119
	v_exp_f32_e32 v126, v120
	v_mul_f32_e32 v120, v121, v157
	v_exp_f32_e32 v118, v118
	v_exp_f32_e32 v121, v120
	v_add_f32_e32 v119, 1.0, v119
	v_rcp_f32_e32 v120, v119
	v_add_f32_e32 v118, 1.0, v118
	v_add_f32_e32 v119, 1.0, v126
	v_add_f32_e32 v121, 1.0, v121
	v_rcp_f32_e32 v118, v118
	v_rcp_f32_e32 v119, v119
	v_rcp_f32_e32 v121, v121
	v_pk_mul_f32 v[114:115], v[114:115], v[174:175] op_sel_hi:[1,0]
	v_pk_mul_f32 v[122:123], v[122:123], v[174:175] op_sel_hi:[1,0]
	v_pk_mul_f32 v[114:115], v[114:115], v[178:179]
	v_pk_mul_f32 v[124:125], v[124:125], v[174:175] op_sel_hi:[1,0]
	v_pk_mul_f32 v[116:117], v[116:117], v[174:175] op_sel_hi:[1,0]
	v_pk_mul_f32 v[122:123], v[122:123], v[176:177]
	v_pk_mul_f32 v[124:125], v[124:125], v[118:119]
	v_pk_mul_f32 v[116:117], v[116:117], v[120:121]
	v_cvt_pk_bf16_f32 v120, v114, v115
	v_mov_b64_e32 v[114:115], s[24:25]
	v_cvt_pk_bf16_f32 v118, v122, v123
	v_cvt_pk_bf16_f32 v119, v124, v125
	v_cvt_pk_bf16_f32 v121, v116, v117
	v_mad_i64_i32 v[122:123], s[4:5], v160, s83, v[114:115]
	v_lshlrev_b64 v[116:117], 1, v[172:173]
	v_mul_f32_e32 v124, 0xbfb8aa3b, v181
	v_mul_f32_e32 v125, v110, v124
	v_lshl_add_u64 v[122:123], v[122:123], 0, v[116:117]
	v_exp_f32_e32 v125, v125
	global_store_dwordx4 v[122:123], v[118:121], off nt
	s_andn2_b64 vcc, exec, s[0:1]
	s_mov_b64 s[0:1], -1
	v_mul_f32_e32 v120, v102, v124
	v_exp_f32_e32 v121, v120
	v_mul_f32_e32 v120, v111, v124
	v_exp_f32_e32 v123, v120
	v_add_f32_e32 v119, 1.0, v125
	v_rcp_f32_e32 v120, v119
	v_add_f32_e32 v119, 1.0, v121
	v_rcp_f32_e32 v122, v119
; DI u32x4 pk8(f32x4 a, f32x4 b) { u32x4 w; w.x = pk2(a[0], a[1]); w.y = pk2(a[2], a[3]); w.z = pk2(b[0], b[1]); w.w = pk2(b[2], b[3]); return w; }
;     DI void operator()(const Acc& acc, const pg8::Unit& u, int wr, int wc, int fr, int fq) const {
;     ...
;         for (int ai = 0; ai < 2; ++ai)
; #pragma unroll
;             for (int m = 0; m < 4; ++m) {
;                 const int row = u.pm * 256 + ai * 128 + wr * 64 + m * 16 + fr;
;                 const float rs = rsv[ai][m];
;                 f32x4 h0, h1;
;                 const float rs2 = rs * rs, nrl = -rs * LOG2E;
; #pragma unroll
;                 for (int i = 0; i < 4; ++i) {
;                     const float a0 = acc[ai][0][m][0][i], a1 = acc[ai][0][m][1][i];
;                     h0[i] = (a0 * acc[ai][1][m][0][i]) * rs2 * __builtin_amdgcn_rcpf(1.0f + __builtin_amdgcn_exp2f(a0 * nrl));
;                     h1[i] = (a1 * acc[ai][1][m][1][i]) * rs2 * __builtin_amdgcn_rcpf(1.0f + __builtin_amdgcn_exp2f(a1 * nrl));
;                 }
;                 __builtin_nontemporal_store(pk8(h0, h1), (u32x4*)(HID + (size_t)row * FH + colb));
	v_add_f32_e32 v119, 1.0, v123
	v_rcp_f32_e32 v121, v119
	v_mul_f32_e32 v119, v103, v124
	v_exp_f32_e32 v119, v119
	v_mul_f32_e32 v102, v112, v124
	v_mul_f32_e32 v118, v181, v181
	v_add_f32_e32 v110, 1.0, v119
	v_rcp_f32_e32 v123, v110
	v_exp_f32_e32 v110, v102
	v_mul_f32_e32 v102, v104, v124
	v_exp_f32_e32 v104, v102
	v_pk_mul_f32 v[98:99], v[98:99], v[118:119] op_sel_hi:[1,0]
	v_pk_mul_f32 v[108:109], v[108:109], v[118:119] op_sel_hi:[1,0]
	v_pk_mul_f32 v[102:103], v[98:99], v[122:123]
	v_add_f32_e32 v99, 1.0, v104
	v_mul_f32_e32 v104, v113, v124
	v_add_f32_e32 v98, 1.0, v110
	v_exp_f32_e32 v110, v104
	v_mul_f32_e32 v104, v105, v124
	v_exp_f32_e32 v105, v104
	v_rcp_f32_e32 v104, v99
	v_add_f32_e32 v99, 1.0, v110
	v_rcp_f32_e32 v98, v98
	v_rcp_f32_e32 v99, v99
	v_add_f32_e32 v105, 1.0, v105
	v_rcp_f32_e32 v105, v105
	v_pk_mul_f32 v[106:107], v[106:107], v[118:119] op_sel_hi:[1,0]
	v_pk_mul_f32 v[108:109], v[108:109], v[98:99]
	v_pk_mul_f32 v[98:99], v[100:101], v[118:119] op_sel_hi:[1,0]
	v_pk_mul_f32 v[106:107], v[106:107], v[120:121]
	v_pk_mul_f32 v[104:105], v[98:99], v[104:105]
	v_cvt_pk_bf16_f32 v100, v102, v103
	v_cvt_pk_bf16_f32 v101, v104, v105
	v_mad_i64_i32 v[102:103], s[4:5], v158, s83, v[114:115]
	v_mul_f32_e32 v104, 0xbfb8aa3b, v175
	v_cvt_pk_bf16_f32 v98, v106, v107
	v_cvt_pk_bf16_f32 v99, v108, v109
	v_mul_f32_e32 v105, v94, v104
	v_lshl_add_u64 v[102:103], v[102:103], 0, v[116:117]
	v_exp_f32_e32 v105, v105
	global_store_dwordx4 v[102:103], v[98:101], off nt
	s_nop 1
	v_mul_f32_e32 v100, v86, v104
	v_exp_f32_e32 v101, v100
	v_mul_f32_e32 v100, v95, v104
	v_exp_f32_e32 v103, v100
	v_add_f32_e32 v99, 1.0, v105
	v_rcp_f32_e32 v100, v99
	v_add_f32_e32 v99, 1.0, v101
	v_rcp_f32_e32 v102, v99
	v_add_f32_e32 v99, 1.0, v103
	v_rcp_f32_e32 v101, v99
	v_mul_f32_e32 v99, v87, v104
	v_exp_f32_e32 v99, v99
	v_mul_f32_e32 v86, v96, v104
	v_mul_f32_e32 v98, v175, v175
	v_add_f32_e32 v94, 1.0, v99
	v_rcp_f32_e32 v103, v94
	v_exp_f32_e32 v94, v86
	v_mul_f32_e32 v86, v88, v104
	v_exp_f32_e32 v88, v86
	v_pk_mul_f32 v[82:83], v[82:83], v[98:99] op_sel_hi:[1,0]
	v_pk_mul_f32 v[92:93], v[92:93], v[98:99] op_sel_hi:[1,0]
	v_pk_mul_f32 v[86:87], v[82:83], v[102:103]
	v_add_f32_e32 v83, 1.0, v88
	v_mul_f32_e32 v88, v97, v104
	v_add_f32_e32 v82, 1.0, v94
	v_exp_f32_e32 v94, v88
	v_mul_f32_e32 v88, v89, v104
	v_exp_f32_e32 v89, v88
	v_rcp_f32_e32 v88, v83
	v_add_f32_e32 v83, 1.0, v94
	v_rcp_f32_e32 v82, v82
	v_rcp_f32_e32 v83, v83
	v_add_f32_e32 v89, 1.0, v89
	v_rcp_f32_e32 v89, v89
	v_pk_mul_f32 v[90:91], v[90:91], v[98:99] op_sel_hi:[1,0]
	v_pk_mul_f32 v[92:93], v[92:93], v[82:83]
	v_pk_mul_f32 v[82:83], v[84:85], v[98:99] op_sel_hi:[1,0]
	v_pk_mul_f32 v[90:91], v[90:91], v[100:101]
	v_pk_mul_f32 v[88:89], v[82:83], v[88:89]
	v_cvt_pk_bf16_f32 v84, v86, v87
	v_cvt_pk_bf16_f32 v85, v88, v89
	v_mad_i64_i32 v[86:87], s[4:5], v156, s83, v[114:115]
	v_mul_f32_e32 v88, 0xbfb8aa3b, v151
	v_cvt_pk_bf16_f32 v82, v90, v91
	v_cvt_pk_bf16_f32 v83, v92, v93
	v_mul_f32_e32 v89, v78, v88
	v_lshl_add_u64 v[86:87], v[86:87], 0, v[116:117]
	v_exp_f32_e32 v89, v89
	global_store_dwordx4 v[86:87], v[82:85], off nt
	s_nop 1
	v_mul_f32_e32 v84, v70, v88
	v_exp_f32_e32 v85, v84
	v_mul_f32_e32 v84, v79, v88
	v_exp_f32_e32 v87, v84
	v_add_f32_e32 v83, 1.0, v89
	v_rcp_f32_e32 v84, v83
	v_add_f32_e32 v83, 1.0, v85
	v_rcp_f32_e32 v86, v83
	v_add_f32_e32 v83, 1.0, v87
	v_rcp_f32_e32 v85, v83
	v_mul_f32_e32 v83, v71, v88
	v_exp_f32_e32 v83, v83
	v_mul_f32_e32 v70, v80, v88
	v_mul_f32_e32 v82, v151, v151
	v_add_f32_e32 v78, 1.0, v83
	v_rcp_f32_e32 v87, v78
	v_exp_f32_e32 v78, v70
	v_mul_f32_e32 v70, v72, v88
	v_exp_f32_e32 v72, v70
	v_pk_mul_f32 v[66:67], v[66:67], v[82:83] op_sel_hi:[1,0]
	v_pk_mul_f32 v[76:77], v[76:77], v[82:83] op_sel_hi:[1,0]
	v_pk_mul_f32 v[70:71], v[66:67], v[86:87]
	v_add_f32_e32 v67, 1.0, v72
	v_mul_f32_e32 v72, v81, v88
	v_add_f32_e32 v66, 1.0, v78
	v_exp_f32_e32 v78, v72
	v_mul_f32_e32 v72, v73, v88
	v_exp_f32_e32 v73, v72
	v_rcp_f32_e32 v72, v67
	v_add_f32_e32 v67, 1.0, v78
	v_rcp_f32_e32 v66, v66
	v_rcp_f32_e32 v67, v67
	v_add_f32_e32 v73, 1.0, v73
	v_rcp_f32_e32 v73, v73
	v_pk_mul_f32 v[74:75], v[74:75], v[82:83] op_sel_hi:[1,0]
	v_pk_mul_f32 v[76:77], v[76:77], v[66:67]
	v_pk_mul_f32 v[66:67], v[68:69], v[82:83] op_sel_hi:[1,0]
	v_pk_mul_f32 v[74:75], v[74:75], v[84:85]
	v_pk_mul_f32 v[72:73], v[66:67], v[72:73]
	v_cvt_pk_bf16_f32 v68, v70, v71
	v_cvt_pk_bf16_f32 v69, v72, v73
	v_mad_i64_i32 v[70:71], s[4:5], v154, s83, v[114:115]
	v_mul_f32_e32 v72, 0xbfb8aa3b, v153
	v_cvt_pk_bf16_f32 v66, v74, v75
	v_cvt_pk_bf16_f32 v67, v76, v77
	v_mul_f32_e32 v73, v62, v72
	v_lshl_add_u64 v[70:71], v[70:71], 0, v[116:117]
	v_exp_f32_e32 v73, v73
	global_store_dwordx4 v[70:71], v[66:69], off nt
	s_nop 1
	v_mul_f32_e32 v68, v54, v72
	v_exp_f32_e32 v69, v68
	v_mul_f32_e32 v68, v63, v72
	v_exp_f32_e32 v71, v68
	v_add_f32_e32 v67, 1.0, v73
	v_rcp_f32_e32 v68, v67
	v_add_f32_e32 v67, 1.0, v69
	v_rcp_f32_e32 v70, v67
	v_add_f32_e32 v67, 1.0, v71
	v_rcp_f32_e32 v69, v67
	v_mul_f32_e32 v67, v55, v72
	v_exp_f32_e32 v67, v67
	v_mul_f32_e32 v54, v64, v72
	v_mul_f32_e32 v66, v153, v153
	v_add_f32_e32 v62, 1.0, v67
	v_rcp_f32_e32 v71, v62
	v_exp_f32_e32 v62, v54
	v_mul_f32_e32 v54, v56, v72
	v_exp_f32_e32 v56, v54
	v_pk_mul_f32 v[50:51], v[50:51], v[66:67] op_sel_hi:[1,0]
	v_pk_mul_f32 v[60:61], v[60:61], v[66:67] op_sel_hi:[1,0]
	v_pk_mul_f32 v[54:55], v[50:51], v[70:71]
	v_add_f32_e32 v51, 1.0, v56
	v_mul_f32_e32 v56, v65, v72
	v_add_f32_e32 v50, 1.0, v62
	v_exp_f32_e32 v62, v56
	v_mul_f32_e32 v56, v57, v72
	v_exp_f32_e32 v57, v56
; DI u32x4 pk8(f32x4 a, f32x4 b) { u32x4 w; w.x = pk2(a[0], a[1]); w.y = pk2(a[2], a[3]); w.z = pk2(b[0], b[1]); w.w = pk2(b[2], b[3]); return w; }
; #define PG8_BAR __builtin_amdgcn_s_barrier()
; template <class Epi, bool ALIGN_EPI>
; __device__ __forceinline__ void gemm_phase(LAS unsigned char* lds, const Gemm g, const StaticOrder& S, const Epi& E) {
;     ...
;         if (!has_next) break;
; #pragma unroll
;         for (int a = 0; a < 2; ++a)
; #pragma unroll
;             for (int b = 0; b < 2; ++b)
; #pragma unroll
;                 for (int m = 0; m < 4; ++m)
; #pragma unroll
;                     for (int n = 0; n < 2; ++n) acc[a][b][m][n] = (f32x4){0.f, 0.f, 0.f, 0.f};
;         cur = nxt; cA = nA; cB = nB; ++ui;
;         if constexpr (ALIGN_EPI) { if (wr == 1) PG8_BAR; }
;     DI void operator()(const Acc& acc, const pg8::Unit& u, int wr, int wc, int fr, int fq) const {
;     ...
;         for (int ai = 0; ai < 2; ++ai)
; #pragma unroll
;             for (int m = 0; m < 4; ++m) {
;                 const int row = u.pm * 256 + ai * 128 + wr * 64 + m * 16 + fr;
;                 const float rs = rsv[ai][m];
;                 f32x4 h0, h1;
;                 const float rs2 = rs * rs, nrl = -rs * LOG2E;
; #pragma unroll
;                 for (int i = 0; i < 4; ++i) {
;                     const float a0 = acc[ai][0][m][0][i], a1 = acc[ai][0][m][1][i];
;                     h0[i] = (a0 * acc[ai][1][m][0][i]) * rs2 * __builtin_amdgcn_rcpf(1.0f + __builtin_amdgcn_exp2f(a0 * nrl));
;                     h1[i] = (a1 * acc[ai][1][m][1][i]) * rs2 * __builtin_amdgcn_rcpf(1.0f + __builtin_amdgcn_exp2f(a1 * nrl));
;                 }
;                 __builtin_nontemporal_store(pk8(h0, h1), (u32x4*)(HID + (size_t)row * FH + colb));
	v_rcp_f32_e32 v56, v51
	v_add_f32_e32 v51, 1.0, v62
	v_rcp_f32_e32 v50, v50
	v_rcp_f32_e32 v51, v51
	v_add_f32_e32 v57, 1.0, v57
	v_rcp_f32_e32 v57, v57
	v_pk_mul_f32 v[58:59], v[58:59], v[66:67] op_sel_hi:[1,0]
	v_pk_mul_f32 v[60:61], v[60:61], v[50:51]
	v_pk_mul_f32 v[50:51], v[52:53], v[66:67] op_sel_hi:[1,0]
	v_pk_mul_f32 v[58:59], v[58:59], v[68:69]
	v_pk_mul_f32 v[56:57], v[50:51], v[56:57]
	v_cvt_pk_bf16_f32 v52, v54, v55
	v_cvt_pk_bf16_f32 v53, v56, v57
	v_mad_i64_i32 v[54:55], s[4:5], v152, s83, v[114:115]
	v_mul_f32_e32 v56, 0xbfb8aa3b, v155
	v_cvt_pk_bf16_f32 v50, v58, v59
	v_cvt_pk_bf16_f32 v51, v60, v61
	v_mul_f32_e32 v57, v46, v56
	v_lshl_add_u64 v[54:55], v[54:55], 0, v[116:117]
	v_exp_f32_e32 v57, v57
	global_store_dwordx4 v[54:55], v[50:53], off nt
	s_nop 1
	v_mul_f32_e32 v52, v38, v56
	v_exp_f32_e32 v53, v52
	v_mul_f32_e32 v52, v47, v56
	v_exp_f32_e32 v55, v52
	v_add_f32_e32 v51, 1.0, v57
	v_rcp_f32_e32 v52, v51
	v_add_f32_e32 v51, 1.0, v53
	v_rcp_f32_e32 v54, v51
	v_add_f32_e32 v51, 1.0, v55
	v_rcp_f32_e32 v53, v51
	v_mul_f32_e32 v51, v39, v56
	v_exp_f32_e32 v51, v51
	v_mul_f32_e32 v38, v48, v56
	v_mul_f32_e32 v50, v155, v155
	v_add_f32_e32 v46, 1.0, v51
	v_rcp_f32_e32 v55, v46
	v_exp_f32_e32 v46, v38
	v_mul_f32_e32 v38, v40, v56
	v_exp_f32_e32 v40, v38
	v_pk_mul_f32 v[34:35], v[34:35], v[50:51] op_sel_hi:[1,0]
	v_pk_mul_f32 v[44:45], v[44:45], v[50:51] op_sel_hi:[1,0]
	v_pk_mul_f32 v[38:39], v[34:35], v[54:55]
	v_add_f32_e32 v35, 1.0, v40
	v_mul_f32_e32 v40, v49, v56
	v_add_f32_e32 v34, 1.0, v46
	v_exp_f32_e32 v46, v40
	v_mul_f32_e32 v40, v41, v56
	v_exp_f32_e32 v41, v40
	v_rcp_f32_e32 v40, v35
	v_add_f32_e32 v35, 1.0, v46
	v_rcp_f32_e32 v34, v34
	v_rcp_f32_e32 v35, v35
	v_add_f32_e32 v41, 1.0, v41
	v_rcp_f32_e32 v41, v41
	v_pk_mul_f32 v[42:43], v[42:43], v[50:51] op_sel_hi:[1,0]
	v_pk_mul_f32 v[44:45], v[44:45], v[34:35]
	v_pk_mul_f32 v[34:35], v[36:37], v[50:51] op_sel_hi:[1,0]
	v_pk_mul_f32 v[42:43], v[42:43], v[52:53]
	v_pk_mul_f32 v[40:41], v[34:35], v[40:41]
	v_cvt_pk_bf16_f32 v36, v38, v39
	v_cvt_pk_bf16_f32 v37, v40, v41
	v_mad_i64_i32 v[38:39], s[4:5], v150, s83, v[114:115]
	v_mul_f32_e32 v40, 0xbfb8aa3b, v149
	v_cvt_pk_bf16_f32 v34, v42, v43
	v_cvt_pk_bf16_f32 v35, v44, v45
	v_mul_f32_e32 v41, v30, v40
	v_lshl_add_u64 v[38:39], v[38:39], 0, v[116:117]
	v_exp_f32_e32 v41, v41
	global_store_dwordx4 v[38:39], v[34:37], off nt
	s_nop 1
	v_mul_f32_e32 v36, v22, v40
	v_exp_f32_e32 v37, v36
	v_mul_f32_e32 v36, v31, v40
	v_exp_f32_e32 v39, v36
	v_add_f32_e32 v35, 1.0, v41
	v_rcp_f32_e32 v36, v35
	v_add_f32_e32 v35, 1.0, v37
	v_rcp_f32_e32 v38, v35
	v_add_f32_e32 v35, 1.0, v39
	v_rcp_f32_e32 v37, v35
	v_mul_f32_e32 v35, v23, v40
	v_exp_f32_e32 v35, v35
	v_mul_f32_e32 v22, v32, v40
	v_mul_f32_e32 v34, v149, v149
	v_add_f32_e32 v30, 1.0, v35
	v_rcp_f32_e32 v39, v30
	v_exp_f32_e32 v30, v22
	v_mul_f32_e32 v22, v24, v40
	v_exp_f32_e32 v24, v22
	v_pk_mul_f32 v[18:19], v[18:19], v[34:35] op_sel_hi:[1,0]
	v_pk_mul_f32 v[28:29], v[28:29], v[34:35] op_sel_hi:[1,0]
	v_pk_mul_f32 v[22:23], v[18:19], v[38:39]
	v_add_f32_e32 v19, 1.0, v24
	v_mul_f32_e32 v24, v33, v40
	v_add_f32_e32 v18, 1.0, v30
	v_exp_f32_e32 v30, v24
	v_mul_f32_e32 v24, v25, v40
	v_exp_f32_e32 v25, v24
	v_rcp_f32_e32 v24, v19
	v_add_f32_e32 v19, 1.0, v30
	v_rcp_f32_e32 v18, v18
	v_rcp_f32_e32 v19, v19
	v_add_f32_e32 v25, 1.0, v25
	v_rcp_f32_e32 v25, v25
	v_pk_mul_f32 v[26:27], v[26:27], v[34:35] op_sel_hi:[1,0]
	v_pk_mul_f32 v[28:29], v[28:29], v[18:19]
	v_pk_mul_f32 v[18:19], v[20:21], v[34:35] op_sel_hi:[1,0]
	v_pk_mul_f32 v[26:27], v[26:27], v[36:37]
	v_pk_mul_f32 v[24:25], v[18:19], v[24:25]
	v_cvt_pk_bf16_f32 v20, v22, v23
	v_cvt_pk_bf16_f32 v21, v24, v25
	v_mad_i64_i32 v[22:23], s[4:5], v148, s83, v[114:115]
	v_mul_f32_e32 v24, 0xbfb8aa3b, v147
	v_cvt_pk_bf16_f32 v18, v26, v27
	v_cvt_pk_bf16_f32 v19, v28, v29
	v_mul_f32_e32 v25, v14, v24
	v_lshl_add_u64 v[22:23], v[22:23], 0, v[116:117]
	v_exp_f32_e32 v25, v25
	global_store_dwordx4 v[22:23], v[18:21], off nt
	s_nop 1
	v_mul_f32_e32 v20, v6, v24
	v_exp_f32_e32 v21, v20
	v_mul_f32_e32 v20, v15, v24
	v_exp_f32_e32 v23, v20
	v_add_f32_e32 v19, 1.0, v25
	v_rcp_f32_e32 v20, v19
	v_add_f32_e32 v19, 1.0, v21
	v_rcp_f32_e32 v22, v19
	v_add_f32_e32 v19, 1.0, v23
	v_rcp_f32_e32 v21, v19
	v_mul_f32_e32 v19, v7, v24
	v_exp_f32_e32 v19, v19
	v_mul_f32_e32 v6, v16, v24
	v_mul_f32_e32 v18, v147, v147
	v_add_f32_e32 v14, 1.0, v19
	v_rcp_f32_e32 v23, v14
	v_exp_f32_e32 v14, v6
	v_mul_f32_e32 v6, v8, v24
	v_exp_f32_e32 v8, v6
	v_pk_mul_f32 v[2:3], v[2:3], v[18:19] op_sel_hi:[1,0]
	v_pk_mul_f32 v[12:13], v[12:13], v[18:19] op_sel_hi:[1,0]
	v_pk_mul_f32 v[6:7], v[2:3], v[22:23]
	v_add_f32_e32 v3, 1.0, v8
	v_mul_f32_e32 v8, v17, v24
	v_add_f32_e32 v2, 1.0, v14
	v_exp_f32_e32 v14, v8
	v_mul_f32_e32 v8, v9, v24
	v_exp_f32_e32 v9, v8
	v_rcp_f32_e32 v8, v3
	v_add_f32_e32 v3, 1.0, v14
	v_rcp_f32_e32 v2, v2
	v_rcp_f32_e32 v3, v3
	v_add_f32_e32 v9, 1.0, v9
	v_rcp_f32_e32 v9, v9
	v_pk_mul_f32 v[10:11], v[10:11], v[18:19] op_sel_hi:[1,0]
	v_pk_mul_f32 v[12:13], v[12:13], v[2:3]
	v_pk_mul_f32 v[2:3], v[4:5], v[18:19] op_sel_hi:[1,0]
	v_pk_mul_f32 v[10:11], v[10:11], v[20:21]
	v_pk_mul_f32 v[8:9], v[2:3], v[8:9]
	v_cvt_pk_bf16_f32 v4, v6, v7
	v_mad_i64_i32 v[6:7], s[4:5], v146, s83, v[114:115]
	v_cvt_pk_bf16_f32 v2, v10, v11
	v_cvt_pk_bf16_f32 v3, v12, v13
	v_cvt_pk_bf16_f32 v5, v8, v9
	v_lshl_add_u64 v[6:7], v[6:7], 0, v[116:117]
	global_store_dwordx4 v[6:7], v[2:5], off nt
	s_cbranch_vccnz .LBB0_605
	s_andn2_b64 vcc, exec, s[54:55]
	s_cbranch_vccnz .LBB0_604
	s_barrier
	s_branch .LBB0_604

; DI u32x4 pk8(f32x4 a, f32x4 b) { u32x4 w; w.x = pk2(a[0], a[1]); w.y = pk2(a[2], a[3]); w.z = pk2(b[0], b[1]); w.w = pk2(b[2], b[3]); return w; }
; DI float row_rstd(const float* SS, int row) { return rsqrtf(SS[row] * (1.0f / 1024.0f) + 1e-6f); }
;     DI void operator()(const Acc& acc, const pg8::Unit& u, int wr, int wc, int fr, int fq) const {
;         const int typ = u.pn >> 1, ph = u.pn & 1;
;         bf16_t* O = QKVUS + (size_t)typ * ((size_t)MT * MW);
;         const bool samp = (u.pm == 128);
;         const bool keep = samp || ((u.pm & 15) >= 14);
;         float rsv[2][4];
; #pragma unroll
;         for (int ai = 0; ai < 2; ++ai)
; #pragma unroll
;             for (int m = 0; m < 4; ++m) rsv[ai][m] = row_rstd(SS, u.pm * 256 + ai * 128 + wr * 64 + m * 16 + fr);
;     ...
;         } else {
; #pragma unroll
;             for (int ai = 0; ai < 2; ++ai)
; #pragma unroll
;                 for (int m = 0; m < 4; ++m) {
;                     const int row = u.pm * 256 + ai * 128 + wr * 64 + m * 16 + fr;
;                     const float rs = rsv[ai][m];
;                     float s1 = 0.f, s2 = 0.f;
; #pragma unroll
;                     for (int bj = 0; bj < 2; ++bj) {
;                         const f32x4 o0 = acc[ai][bj][m][0] * rs, o1 = acc[ai][bj][m][1] * rs;
;                         const int col = ph * 256 + bj * 128 + wc * 32 + fq * 8;
;                         *(u32x4*)(O + (size_t)row * MW + col) = pk8(o0, o1);
;                         if (typ == 4) {
;                             s1 += (o0[0] + o0[1]) + (o0[2] + o0[3]) + (o1[0] + o1[1]) + (o1[2] + o1[3]);
;                             s2 += (o0[0] * o0[0] + o0[1] * o0[1]) + (o0[2] * o0[2] + o0[3] * o0[3]) + (o1[0] * o1[0] + o1[1] * o1[1]) + (o1[2] * o1[2] + o1[3] * o1[3]);
.LBB0_790:
	s_ashr_i32 s55, s86, 1
	s_mul_i32 s5, s55, 0x2040000
	s_mul_hi_i32 s4, s55, 0x2040000
	s_add_u32 s88, s24, s5
	s_addc_u32 s89, s25, s4
	s_and_b32 s4, s84, 14
	s_cmp_eq_u32 s4, 14
	s_cselect_b64 s[6:7], -1, 0
	s_lshl_b32 s73, s84, 8
	v_add_u32_e32 v180, s73, v216
	v_ashrrev_i32_e32 v181, 31, v180
	v_lshl_add_u64 v[130:131], v[180:181], 2, s[16:17]
	global_load_dword v240, v[130:131], off
	v_or_b32_e32 v192, 16, v180
	v_ashrrev_i32_e32 v193, 31, v192
	v_or_b32_e32 v188, 32, v180
	v_ashrrev_i32_e32 v189, 31, v188
	v_or_b32_e32 v184, 48, v180
	v_ashrrev_i32_e32 v185, 31, v184
	v_add_u32_e32 v178, 0x80, v180
	v_ashrrev_i32_e32 v179, 31, v178
	v_add_u32_e32 v174, 0x90, v180
	v_ashrrev_i32_e32 v175, 31, v174
	v_add_u32_e32 v170, 0xa0, v180
	v_ashrrev_i32_e32 v171, 31, v170
	v_add_u32_e32 v166, 0xb0, v180
	v_ashrrev_i32_e32 v167, 31, v166
	s_and_b32 s79, s86, 1
	s_cmpk_eq_i32 s84, 0x80
	s_cselect_b64 s[4:5], -1, 0
	s_or_b64 s[90:91], s[4:5], s[6:7]
	s_mov_b64 s[6:7], -1
	s_cmp_lt_i32 s55, 2
	v_lshlrev_b64 v[198:199], 10, v[180:181]
	v_lshl_add_u64 v[130:131], v[192:193], 2, s[16:17]
	global_load_dword v241, v[130:131], off
	v_lshl_add_u64 v[130:131], v[188:189], 2, s[16:17]
	global_load_dword v242, v[130:131], off
	v_lshl_add_u64 v[130:131], v[184:185], 2, s[16:17]
	global_load_dword v243, v[130:131], off
	v_lshl_add_u64 v[130:131], v[178:179], 2, s[16:17]
	global_load_dword v244, v[130:131], off
	v_lshl_add_u64 v[130:131], v[174:175], 2, s[16:17]
	global_load_dword v245, v[130:131], off
	v_lshl_add_u64 v[130:131], v[170:171], 2, s[16:17]
	global_load_dword v246, v[130:131], off
	v_lshl_add_u64 v[130:131], v[166:167], 2, s[16:17]
	global_load_dword v248, v[130:131], off
	s_waitcnt vmcnt(0)
	v_fmamk_f32 v130, v240, 0x3a800000, v223
	s_nop 0
	v_rsq_f32_e32 v130, v130
	s_nop 0
	v_mov_b32_e32 v196, v130
	v_fmamk_f32 v130, v241, 0x3a800000, v223
	s_nop 0
	v_rsq_f32_e32 v130, v130
	s_nop 0
	v_mov_b32_e32 v194, v130
	v_fmamk_f32 v130, v242, 0x3a800000, v223
	s_nop 0
	v_rsq_f32_e32 v130, v130
	s_nop 0
	v_mov_b32_e32 v190, v130
	v_fmamk_f32 v130, v243, 0x3a800000, v223
	s_nop 0
	v_rsq_f32_e32 v130, v130
	s_nop 0
	v_mov_b32_e32 v186, v130
	v_fmamk_f32 v130, v244, 0x3a800000, v223
	s_nop 0
	v_rsq_f32_e32 v130, v130
	s_nop 0
	v_mov_b32_e32 v182, v130
	v_fmamk_f32 v130, v245, 0x3a800000, v223
	s_nop 0
	v_rsq_f32_e32 v130, v130
	s_nop 0
	v_mov_b32_e32 v176, v130
	v_fmamk_f32 v130, v246, 0x3a800000, v223
	s_nop 0
	v_rsq_f32_e32 v130, v130
	s_nop 0
	v_mov_b32_e32 v172, v130
	v_fmamk_f32 v130, v248, 0x3a800000, v223
	s_nop 0
	v_rsq_f32_e32 v130, v130
	s_nop 0
	v_mov_b32_e32 v168, v130
	s_cbranch_scc1 .LBB0_895
	v_lshl_or_b32 v138, s79, 8, v219
	s_cmp_eq_u32 s55, 4
	s_cselect_b64 s[96:97], -1, 0
	v_lshl_add_u64 v[144:145], s[88:89], 0, v[198:199]
	v_pk_mul_f32 v[132:133], v[128:129], v[196:197] op_sel_hi:[1,0]
	v_pk_mul_f32 v[130:131], v[126:127], v[196:197] op_sel_hi:[1,0]
	v_pk_mul_f32 v[136:137], v[124:125], v[196:197] op_sel_hi:[1,0]
	v_pk_mul_f32 v[134:135], v[122:123], v[196:197] op_sel_hi:[1,0]
	v_lshlrev_b32_e32 v154, 1, v138
	v_cvt_pk_bf16_f32 v140, v130, v131
	v_cvt_pk_bf16_f32 v141, v132, v133
	v_cvt_pk_bf16_f32 v142, v134, v135
	v_cvt_pk_bf16_f32 v143, v136, v137
	v_lshl_add_u64 v[202:203], v[144:145], 0, v[154:155]
	s_and_b64 vcc, exec, s[96:97]
	global_store_dwordx4 v[202:203], v[140:143], off
	s_cbranch_vccz .LBB0_793
	s_nop 0
	v_mov_b32_e32 v140, v131
	v_mov_b32_e32 v141, v132
	v_mov_b32_e32 v142, v130
	v_mov_b32_e32 v143, v133
	v_pk_add_f32 v[140:141], v[140:141], v[142:143]
	v_mul_f32_e32 v142, v130, v130
	v_pk_fma_f32 v[142:143], v[130:131], v[130:131], v[142:143] op_sel_hi:[1,1,0]
	v_mul_f32_e32 v139, v134, v134
	v_mul_f32_e32 v142, v132, v132
	v_pk_fma_f32 v[144:145], v[132:133], v[132:133], v[142:143] op_sel_hi:[1,1,0]
	v_mov_b32_e32 v142, v136
	v_mov_b32_e32 v144, v137
	v_pk_add_f32 v[142:143], v[142:143], v[144:145]
	v_pk_add_f32 v[144:145], v[134:135], v[134:135] op_sel:[1,0]
	v_pk_mul_f32 v[200:201], v[134:135], v[134:135]
	v_pk_add_f32 v[140:141], v[140:141], v[140:141] op_sel:[0,1] op_sel_hi:[1,0]
	v_mov_b32_e32 v145, v201
	v_mov_b32_e32 v141, v139
	v_pk_add_f32 v[140:141], v[144:145], v[140:141]
	s_nop 0
	v_pk_add_f32 v[140:141], v[140:141], v[142:143]
	v_mul_f32_e32 v142, v136, v136
	v_pk_fma_f32 v[142:143], v[136:137], v[136:137], v[142:143] op_sel_hi:[1,1,0]
	s_nop 0
	v_mov_b32_e32 v142, v155
	v_pk_add_f32 v[142:143], v[140:141], v[142:143]
	s_branch .LBB0_794

; DI u32x4 pk8(f32x4 a, f32x4 b) { u32x4 w; w.x = pk2(a[0], a[1]); w.y = pk2(a[2], a[3]); w.z = pk2(b[0], b[1]); w.w = pk2(b[2], b[3]); return w; }
; DI float row_rstd(const float* SS, int row) { return rsqrtf(SS[row] * (1.0f / 1024.0f) + 1e-6f); }
;     DI void operator()(const Acc& acc, const pg8::Unit& u, int wr, int wc, int fr, int fq) const {
;         const int colb = u.pn * 128 + wc * 32 + fq * 8;
;         float rsv[2][4];
; #pragma unroll
;         for (int ai = 0; ai < 2; ++ai)
; #pragma unroll
;             for (int m = 0; m < 4; ++m) rsv[ai][m] = row_rstd(SS, u.pm * 256 + ai * 128 + wr * 64 + m * 16 + fr);
; #pragma unroll
;         for (int ai = 0; ai < 2; ++ai)
; #pragma unroll
;             for (int m = 0; m < 4; ++m) {
;                 const int row = u.pm * 256 + ai * 128 + wr * 64 + m * 16 + fr;
;                 const float rs = rsv[ai][m];
;                 f32x4 h0, h1;
;                 const float rs2 = rs * rs, nrl = -rs * LOG2E;
; #pragma unroll
;                 for (int i = 0; i < 4; ++i) {
;                     const float a0 = acc[ai][0][m][0][i], a1 = acc[ai][0][m][1][i];
;                     h0[i] = (a0 * acc[ai][1][m][0][i]) * rs2 * __builtin_amdgcn_rcpf(1.0f + __builtin_amdgcn_exp2f(a0 * nrl));
;                     h1[i] = (a1 * acc[ai][1][m][1][i]) * rs2 * __builtin_amdgcn_rcpf(1.0f + __builtin_amdgcn_exp2f(a1 * nrl));
;                 }
;                 __builtin_nontemporal_store(pk8(h0, h1), (u32x4*)(HID + (size_t)row * FH + colb));
.LBB0_1431:
	v_lshl_add_u32 v160, s4, 8, v165
	v_ashrrev_i32_e32 v161, 31, v160
	v_lshl_add_u64 v[146:147], v[160:161], 2, s[20:21]
	v_or_b32_e32 v158, 16, v160
	global_load_dword v161, v[146:147], off
	v_ashrrev_i32_e32 v159, 31, v158
	v_or_b32_e32 v156, 32, v160
	v_or_b32_e32 v154, 48, v160
	v_add_u32_e32 v152, 0x80, v160
	v_add_u32_e32 v150, 0x90, v160
	v_add_u32_e32 v148, 0xa0, v160
	v_add_u32_e32 v146, 0xb0, v160
	v_lshl_add_u64 v[172:173], v[158:159], 2, s[20:21]
	v_ashrrev_i32_e32 v157, 31, v156
	v_ashrrev_i32_e32 v155, 31, v154
	v_ashrrev_i32_e32 v153, 31, v152
	v_ashrrev_i32_e32 v151, 31, v150
	v_ashrrev_i32_e32 v149, 31, v148
	v_ashrrev_i32_e32 v147, 31, v146
	v_lshl_add_u64 v[174:175], v[156:157], 2, s[20:21]
	v_lshl_add_u64 v[176:177], v[154:155], 2, s[20:21]
	v_lshl_add_u64 v[178:179], v[152:153], 2, s[20:21]
	v_lshl_add_u64 v[180:181], v[150:151], 2, s[20:21]
	v_lshl_add_u64 v[182:183], v[148:149], 2, s[20:21]
	v_lshl_add_u64 v[184:185], v[146:147], 2, s[20:21]
	global_load_dword v147, v[172:173], off
	global_load_dword v149, v[174:175], off
	global_load_dword v151, v[176:177], off
	global_load_dword v153, v[178:179], off
	global_load_dword v155, v[180:181], off
	global_load_dword v157, v[182:183], off
	global_load_dword v159, v[184:185], off
	v_lshl_or_b32 v172, s5, 7, v167
	v_pk_mul_f32 v[122:123], v[126:127], v[122:123]
	v_pk_mul_f32 v[116:117], v[120:121], v[116:117]
	v_pk_mul_f32 v[114:115], v[118:119], v[114:115]
	v_pk_mul_f32 v[124:125], v[128:129], v[124:125]
	v_ashrrev_i32_e32 v173, 31, v172
	v_pk_mul_f32 v[106:107], v[110:111], v[106:107]
	v_pk_mul_f32 v[98:99], v[102:103], v[98:99]
	v_pk_mul_f32 v[100:101], v[104:105], v[100:101]
	v_pk_mul_f32 v[108:109], v[112:113], v[108:109]
	v_pk_mul_f32 v[90:91], v[94:95], v[90:91]
	v_pk_mul_f32 v[82:83], v[86:87], v[82:83]
	v_pk_mul_f32 v[84:85], v[88:89], v[84:85]
	v_pk_mul_f32 v[92:93], v[96:97], v[92:93]
	v_pk_mul_f32 v[74:75], v[78:79], v[74:75]
	v_pk_mul_f32 v[66:67], v[70:71], v[66:67]
	v_pk_mul_f32 v[68:69], v[72:73], v[68:69]
	v_pk_mul_f32 v[76:77], v[80:81], v[76:77]
	v_pk_mul_f32 v[58:59], v[62:63], v[58:59]
	v_pk_mul_f32 v[50:51], v[54:55], v[50:51]
	v_pk_mul_f32 v[52:53], v[56:57], v[52:53]
	v_pk_mul_f32 v[60:61], v[64:65], v[60:61]
	v_pk_mul_f32 v[42:43], v[46:47], v[42:43]
	v_pk_mul_f32 v[34:35], v[38:39], v[34:35]
	v_pk_mul_f32 v[36:37], v[40:41], v[36:37]
	v_pk_mul_f32 v[44:45], v[48:49], v[44:45]
	v_pk_mul_f32 v[26:27], v[30:31], v[26:27]
	v_pk_mul_f32 v[18:19], v[22:23], v[18:19]
	v_pk_mul_f32 v[20:21], v[24:25], v[20:21]
	v_pk_mul_f32 v[28:29], v[32:33], v[28:29]
	v_pk_mul_f32 v[10:11], v[14:15], v[10:11]
	v_pk_mul_f32 v[2:3], v[6:7], v[2:3]
	v_pk_mul_f32 v[4:5], v[8:9], v[4:5]
	v_pk_mul_f32 v[12:13], v[16:17], v[12:13]
	s_waitcnt vmcnt(0)
	v_fmamk_f32 v161, v161, 0x3a800000, v171
	v_fmamk_f32 v147, v147, 0x3a800000, v171
	v_fmamk_f32 v149, v149, 0x3a800000, v171
	v_fmamk_f32 v157, v157, 0x3a800000, v171
	v_fmamk_f32 v159, v159, 0x3a800000, v171
	v_rsq_f32_e32 v161, v161
	v_fmamk_f32 v151, v151, 0x3a800000, v171
	v_rsq_f32_e32 v149, v149
	v_rsq_f32_e32 v157, v157
	v_fmamk_f32 v153, v153, 0x3a800000, v171
	v_rsq_f32_e32 v147, v147
	v_rsq_f32_e32 v159, v159
	v_rsq_f32_e32 v151, v151
	v_rsq_f32_e32 v153, v153
	v_fmamk_f32 v155, v155, 0x3a800000, v171
	v_mov_b32_e32 v175, v149
	v_mov_b32_e32 v149, v157
	v_mul_f32_e32 v157, 0xbfb8aa3b, v161
	v_mov_b32_e32 v181, v147
	v_mov_b32_e32 v147, v159
	v_mul_f32_e32 v159, v126, v157
	v_mul_f32_e32 v174, v161, v161
	v_mul_f32_e32 v161, v118, v157
	v_exp_f32_e32 v159, v159
	v_rsq_f32_e32 v155, v155
	v_mul_f32_e32 v176, v127, v157
	v_exp_f32_e32 v161, v161
	v_exp_f32_e32 v177, v176
	v_add_f32_e32 v159, 1.0, v159
	v_rcp_f32_e32 v176, v159
	v_add_f32_e32 v159, 1.0, v161
	v_rcp_f32_e32 v178, v159
	v_add_f32_e32 v159, 1.0, v177
	v_rcp_f32_e32 v177, v159
	v_mul_f32_e32 v159, v119, v157
	v_exp_f32_e32 v159, v159
	v_mul_f32_e32 v119, v120, v157
	v_mul_f32_e32 v120, v129, v157
	v_mul_f32_e32 v118, v128, v157
	v_add_f32_e32 v126, 1.0, v159
	v_rcp_f32_e32 v179, v126
	v_exp_f32_e32 v119, v119
	v_exp_f32_e32 v126, v120
	v_mul_f32_e32 v120, v121, v157
	v_exp_f32_e32 v118, v118
	v_exp_f32_e32 v121, v120
	v_add_f32_e32 v119, 1.0, v119
	v_rcp_f32_e32 v120, v119
	v_add_f32_e32 v118, 1.0, v118
	v_add_f32_e32 v119, 1.0, v126
	v_add_f32_e32 v121, 1.0, v121
	v_rcp_f32_e32 v118, v118
	v_rcp_f32_e32 v119, v119
	v_rcp_f32_e32 v121, v121
	v_pk_mul_f32 v[114:115], v[114:115], v[174:175] op_sel_hi:[1,0]
	v_pk_mul_f32 v[122:123], v[122:123], v[174:175] op_sel_hi:[1,0]
	v_pk_mul_f32 v[114:115], v[114:115], v[178:179]
	v_pk_mul_f32 v[124:125], v[124:125], v[174:175] op_sel_hi:[1,0]
	v_pk_mul_f32 v[116:117], v[116:117], v[174:175] op_sel_hi:[1,0]
	v_pk_mul_f32 v[122:123], v[122:123], v[176:177]
	v_pk_mul_f32 v[124:125], v[124:125], v[118:119]
	v_pk_mul_f32 v[116:117], v[116:117], v[120:121]
	v_cvt_pk_bf16_f32 v120, v114, v115
	v_mov_b64_e32 v[114:115], s[24:25]
	v_cvt_pk_bf16_f32 v118, v122, v123
	v_cvt_pk_bf16_f32 v119, v124, v125
	v_cvt_pk_bf16_f32 v121, v116, v117
	v_mad_i64_i32 v[122:123], s[4:5], v160, s61, v[114:115]
	v_lshlrev_b64 v[116:117], 1, v[172:173]
	v_mul_f32_e32 v124, 0xbfb8aa3b, v181
	v_mul_f32_e32 v125, v110, v124
	v_lshl_add_u64 v[122:123], v[122:123], 0, v[116:117]
	v_exp_f32_e32 v125, v125
	global_store_dwordx4 v[122:123], v[118:121], off nt
	s_andn2_b64 vcc, exec, s[0:1]
	s_mov_b64 s[0:1], -1
	v_mul_f32_e32 v120, v102, v124
	v_exp_f32_e32 v121, v120
	v_mul_f32_e32 v120, v111, v124
	v_exp_f32_e32 v123, v120
	v_add_f32_e32 v119, 1.0, v125
	v_rcp_f32_e32 v120, v119
	v_add_f32_e32 v119, 1.0, v121
	v_rcp_f32_e32 v122, v119
; DI u32x4 pk8(f32x4 a, f32x4 b) { u32x4 w; w.x = pk2(a[0], a[1]); w.y = pk2(a[2], a[3]); w.z = pk2(b[0], b[1]); w.w = pk2(b[2], b[3]); return w; }
; DI float row_rstd(const float* SS, int row) { return rsqrtf(SS[row] * (1.0f / 1024.0f) + 1e-6f); }
;     DI void operator()(const Acc& acc, const pg8::Unit& u, int wr, int wc, int fr, int fq) const {
;         const int colb = u.pn * 128 + wc * 32 + fq * 8;
;         float rsv[2][4];
; #pragma unroll
;         for (int ai = 0; ai < 2; ++ai)
; #pragma unroll
;             for (int m = 0; m < 4; ++m) rsv[ai][m] = row_rstd(SS, u.pm * 256 + ai * 128 + wr * 64 + m * 16 + fr);
; #pragma unroll
;         for (int ai = 0; ai < 2; ++ai)
; #pragma unroll
;             for (int m = 0; m < 4; ++m) {
;                 const int row = u.pm * 256 + ai * 128 + wr * 64 + m * 16 + fr;
;                 const float rs = rsv[ai][m];
;                 f32x4 h0, h1;
;                 const float rs2 = rs * rs, nrl = -rs * LOG2E;
; #pragma unroll
;                 for (int i = 0; i < 4; ++i) {
;                     const float a0 = acc[ai][0][m][0][i], a1 = acc[ai][0][m][1][i];
;                     h0[i] = (a0 * acc[ai][1][m][0][i]) * rs2 * __builtin_amdgcn_rcpf(1.0f + __builtin_amdgcn_exp2f(a0 * nrl));
;                     h1[i] = (a1 * acc[ai][1][m][1][i]) * rs2 * __builtin_amdgcn_rcpf(1.0f + __builtin_amdgcn_exp2f(a1 * nrl));
;                 }
;                 __builtin_nontemporal_store(pk8(h0, h1), (u32x4*)(HID + (size_t)row * FH + colb));
;             }
	v_add_f32_e32 v119, 1.0, v123
	v_rcp_f32_e32 v121, v119
	v_mul_f32_e32 v119, v103, v124
	v_exp_f32_e32 v119, v119
	v_mul_f32_e32 v102, v112, v124
	v_mul_f32_e32 v118, v181, v181
	v_add_f32_e32 v110, 1.0, v119
	v_rcp_f32_e32 v123, v110
	v_exp_f32_e32 v110, v102
	v_mul_f32_e32 v102, v104, v124
	v_exp_f32_e32 v104, v102
	v_pk_mul_f32 v[98:99], v[98:99], v[118:119] op_sel_hi:[1,0]
	v_pk_mul_f32 v[108:109], v[108:109], v[118:119] op_sel_hi:[1,0]
	v_pk_mul_f32 v[102:103], v[98:99], v[122:123]
	v_add_f32_e32 v99, 1.0, v104
	v_mul_f32_e32 v104, v113, v124
	v_add_f32_e32 v98, 1.0, v110
	v_exp_f32_e32 v110, v104
	v_mul_f32_e32 v104, v105, v124
	v_exp_f32_e32 v105, v104
	v_rcp_f32_e32 v104, v99
	v_add_f32_e32 v99, 1.0, v110
	v_rcp_f32_e32 v98, v98
	v_rcp_f32_e32 v99, v99
	v_add_f32_e32 v105, 1.0, v105
	v_rcp_f32_e32 v105, v105
	v_pk_mul_f32 v[106:107], v[106:107], v[118:119] op_sel_hi:[1,0]
	v_pk_mul_f32 v[108:109], v[108:109], v[98:99]
	v_pk_mul_f32 v[98:99], v[100:101], v[118:119] op_sel_hi:[1,0]
	v_pk_mul_f32 v[106:107], v[106:107], v[120:121]
	v_pk_mul_f32 v[104:105], v[98:99], v[104:105]
	v_cvt_pk_bf16_f32 v100, v102, v103
	v_cvt_pk_bf16_f32 v101, v104, v105
	v_mad_i64_i32 v[102:103], s[4:5], v158, s61, v[114:115]
	v_mul_f32_e32 v104, 0xbfb8aa3b, v175
	v_cvt_pk_bf16_f32 v98, v106, v107
	v_cvt_pk_bf16_f32 v99, v108, v109
	v_mul_f32_e32 v105, v94, v104
	v_lshl_add_u64 v[102:103], v[102:103], 0, v[116:117]
	v_exp_f32_e32 v105, v105
	global_store_dwordx4 v[102:103], v[98:101], off nt
	s_nop 1
	v_mul_f32_e32 v100, v86, v104
	v_exp_f32_e32 v101, v100
	v_mul_f32_e32 v100, v95, v104
	v_exp_f32_e32 v103, v100
	v_add_f32_e32 v99, 1.0, v105
	v_rcp_f32_e32 v100, v99
	v_add_f32_e32 v99, 1.0, v101
	v_rcp_f32_e32 v102, v99
	v_add_f32_e32 v99, 1.0, v103
	v_rcp_f32_e32 v101, v99
	v_mul_f32_e32 v99, v87, v104
	v_exp_f32_e32 v99, v99
	v_mul_f32_e32 v86, v96, v104
	v_mul_f32_e32 v98, v175, v175
	v_add_f32_e32 v94, 1.0, v99
	v_rcp_f32_e32 v103, v94
	v_exp_f32_e32 v94, v86
	v_mul_f32_e32 v86, v88, v104
	v_exp_f32_e32 v88, v86
	v_pk_mul_f32 v[82:83], v[82:83], v[98:99] op_sel_hi:[1,0]
	v_pk_mul_f32 v[92:93], v[92:93], v[98:99] op_sel_hi:[1,0]
	v_pk_mul_f32 v[86:87], v[82:83], v[102:103]
	v_add_f32_e32 v83, 1.0, v88
	v_mul_f32_e32 v88, v97, v104
	v_add_f32_e32 v82, 1.0, v94
	v_exp_f32_e32 v94, v88
	v_mul_f32_e32 v88, v89, v104
	v_exp_f32_e32 v89, v88
	v_rcp_f32_e32 v88, v83
	v_add_f32_e32 v83, 1.0, v94
	v_rcp_f32_e32 v82, v82
	v_rcp_f32_e32 v83, v83
	v_add_f32_e32 v89, 1.0, v89
	v_rcp_f32_e32 v89, v89
	v_pk_mul_f32 v[90:91], v[90:91], v[98:99] op_sel_hi:[1,0]
	v_pk_mul_f32 v[92:93], v[92:93], v[82:83]
	v_pk_mul_f32 v[82:83], v[84:85], v[98:99] op_sel_hi:[1,0]
	v_pk_mul_f32 v[90:91], v[90:91], v[100:101]
	v_pk_mul_f32 v[88:89], v[82:83], v[88:89]
	v_cvt_pk_bf16_f32 v84, v86, v87
	v_cvt_pk_bf16_f32 v85, v88, v89
	v_mad_i64_i32 v[86:87], s[4:5], v156, s61, v[114:115]
	v_mul_f32_e32 v88, 0xbfb8aa3b, v151
	v_cvt_pk_bf16_f32 v82, v90, v91
	v_cvt_pk_bf16_f32 v83, v92, v93
	v_mul_f32_e32 v89, v78, v88
	v_lshl_add_u64 v[86:87], v[86:87], 0, v[116:117]
	v_exp_f32_e32 v89, v89
	global_store_dwordx4 v[86:87], v[82:85], off nt
	s_nop 1
	v_mul_f32_e32 v84, v70, v88
	v_exp_f32_e32 v85, v84
	v_mul_f32_e32 v84, v79, v88
	v_exp_f32_e32 v87, v84
	v_add_f32_e32 v83, 1.0, v89
	v_rcp_f32_e32 v84, v83
	v_add_f32_e32 v83, 1.0, v85
	v_rcp_f32_e32 v86, v83
	v_add_f32_e32 v83, 1.0, v87
	v_rcp_f32_e32 v85, v83
	v_mul_f32_e32 v83, v71, v88
	v_exp_f32_e32 v83, v83
	v_mul_f32_e32 v70, v80, v88
	v_mul_f32_e32 v82, v151, v151
	v_add_f32_e32 v78, 1.0, v83
	v_rcp_f32_e32 v87, v78
	v_exp_f32_e32 v78, v70
	v_mul_f32_e32 v70, v72, v88
	v_exp_f32_e32 v72, v70
	v_pk_mul_f32 v[66:67], v[66:67], v[82:83] op_sel_hi:[1,0]
	v_pk_mul_f32 v[76:77], v[76:77], v[82:83] op_sel_hi:[1,0]
	v_pk_mul_f32 v[70:71], v[66:67], v[86:87]
	v_add_f32_e32 v67, 1.0, v72
	v_mul_f32_e32 v72, v81, v88
	v_add_f32_e32 v66, 1.0, v78
	v_exp_f32_e32 v78, v72
	v_mul_f32_e32 v72, v73, v88
	v_exp_f32_e32 v73, v72
	v_rcp_f32_e32 v72, v67
	v_add_f32_e32 v67, 1.0, v78
	v_rcp_f32_e32 v66, v66
	v_rcp_f32_e32 v67, v67
	v_add_f32_e32 v73, 1.0, v73
	v_rcp_f32_e32 v73, v73
	v_pk_mul_f32 v[74:75], v[74:75], v[82:83] op_sel_hi:[1,0]
	v_pk_mul_f32 v[76:77], v[76:77], v[66:67]
	v_pk_mul_f32 v[66:67], v[68:69], v[82:83] op_sel_hi:[1,0]
	v_pk_mul_f32 v[74:75], v[74:75], v[84:85]
	v_pk_mul_f32 v[72:73], v[66:67], v[72:73]
	v_cvt_pk_bf16_f32 v68, v70, v71
	v_cvt_pk_bf16_f32 v69, v72, v73
	v_mad_i64_i32 v[70:71], s[4:5], v154, s61, v[114:115]
	v_mul_f32_e32 v72, 0xbfb8aa3b, v153
	v_cvt_pk_bf16_f32 v66, v74, v75
	v_cvt_pk_bf16_f32 v67, v76, v77
	v_mul_f32_e32 v73, v62, v72
	v_lshl_add_u64 v[70:71], v[70:71], 0, v[116:117]
	v_exp_f32_e32 v73, v73
	global_store_dwordx4 v[70:71], v[66:69], off nt
	s_nop 1
	v_mul_f32_e32 v68, v54, v72
	v_exp_f32_e32 v69, v68
	v_mul_f32_e32 v68, v63, v72
	v_exp_f32_e32 v71, v68
	v_add_f32_e32 v67, 1.0, v73
	v_rcp_f32_e32 v68, v67
	v_add_f32_e32 v67, 1.0, v69
	v_rcp_f32_e32 v70, v67
	v_add_f32_e32 v67, 1.0, v71
	v_rcp_f32_e32 v69, v67
	v_mul_f32_e32 v67, v55, v72
	v_exp_f32_e32 v67, v67
	v_mul_f32_e32 v54, v64, v72
	v_mul_f32_e32 v66, v153, v153
	v_add_f32_e32 v62, 1.0, v67
	v_rcp_f32_e32 v71, v62
	v_exp_f32_e32 v62, v54
	v_mul_f32_e32 v54, v56, v72
	v_exp_f32_e32 v56, v54
	v_pk_mul_f32 v[50:51], v[50:51], v[66:67] op_sel_hi:[1,0]
	v_pk_mul_f32 v[60:61], v[60:61], v[66:67] op_sel_hi:[1,0]
	v_pk_mul_f32 v[54:55], v[50:51], v[70:71]
	v_add_f32_e32 v51, 1.0, v56
	v_mul_f32_e32 v56, v65, v72
	v_add_f32_e32 v50, 1.0, v62
	v_exp_f32_e32 v62, v56
	v_mul_f32_e32 v56, v57, v72
	v_exp_f32_e32 v57, v56
; DI u32x4 pk8(f32x4 a, f32x4 b) { u32x4 w; w.x = pk2(a[0], a[1]); w.y = pk2(a[2], a[3]); w.z = pk2(b[0], b[1]); w.w = pk2(b[2], b[3]); return w; }
; #define PG8_BAR __builtin_amdgcn_s_barrier()
; DI float row_rstd(const float* SS, int row) { return rsqrtf(SS[row] * (1.0f / 1024.0f) + 1e-6f); }
; template <class Epi, bool ALIGN_EPI>
; __device__ __forceinline__ void gemm_phase(LAS unsigned char* lds, const Gemm g, const StaticOrder& S, const Epi& E) {
;     ...
;         if (!has_next) break;
; #pragma unroll
;         for (int a = 0; a < 2; ++a)
; #pragma unroll
;             for (int b = 0; b < 2; ++b)
; #pragma unroll
;                 for (int m = 0; m < 4; ++m)
; #pragma unroll
;                     for (int n = 0; n < 2; ++n) acc[a][b][m][n] = (f32x4){0.f, 0.f, 0.f, 0.f};
;         cur = nxt; cA = nA; cB = nB; ++ui;
;         if constexpr (ALIGN_EPI) { if (wr == 1) PG8_BAR; }
;     DI void operator()(const Acc& acc, const pg8::Unit& u, int wr, int wc, int fr, int fq) const {
;         const int colb = u.pn * 128 + wc * 32 + fq * 8;
;         float rsv[2][4];
; #pragma unroll
;         for (int ai = 0; ai < 2; ++ai)
; #pragma unroll
;             for (int m = 0; m < 4; ++m) rsv[ai][m] = row_rstd(SS, u.pm * 256 + ai * 128 + wr * 64 + m * 16 + fr);
; #pragma unroll
;         for (int ai = 0; ai < 2; ++ai)
; #pragma unroll
;             for (int m = 0; m < 4; ++m) {
;                 const int row = u.pm * 256 + ai * 128 + wr * 64 + m * 16 + fr;
;                 const float rs = rsv[ai][m];
;                 f32x4 h0, h1;
;                 const float rs2 = rs * rs, nrl = -rs * LOG2E;
; #pragma unroll
;                 for (int i = 0; i < 4; ++i) {
;                     const float a0 = acc[ai][0][m][0][i], a1 = acc[ai][0][m][1][i];
;                     h0[i] = (a0 * acc[ai][1][m][0][i]) * rs2 * __builtin_amdgcn_rcpf(1.0f + __builtin_amdgcn_exp2f(a0 * nrl));
;                     h1[i] = (a1 * acc[ai][1][m][1][i]) * rs2 * __builtin_amdgcn_rcpf(1.0f + __builtin_amdgcn_exp2f(a1 * nrl));
;                 }
;                 __builtin_nontemporal_store(pk8(h0, h1), (u32x4*)(HID + (size_t)row * FH + colb));
;             }
	v_rcp_f32_e32 v56, v51
	v_add_f32_e32 v51, 1.0, v62
	v_rcp_f32_e32 v50, v50
	v_rcp_f32_e32 v51, v51
	v_add_f32_e32 v57, 1.0, v57
	v_rcp_f32_e32 v57, v57
	v_pk_mul_f32 v[58:59], v[58:59], v[66:67] op_sel_hi:[1,0]
	v_pk_mul_f32 v[60:61], v[60:61], v[50:51]
	v_pk_mul_f32 v[50:51], v[52:53], v[66:67] op_sel_hi:[1,0]
	v_pk_mul_f32 v[58:59], v[58:59], v[68:69]
	v_pk_mul_f32 v[56:57], v[50:51], v[56:57]
	v_cvt_pk_bf16_f32 v52, v54, v55
	v_cvt_pk_bf16_f32 v53, v56, v57
	v_mad_i64_i32 v[54:55], s[4:5], v152, s61, v[114:115]
	v_mul_f32_e32 v56, 0xbfb8aa3b, v155
	v_cvt_pk_bf16_f32 v50, v58, v59
	v_cvt_pk_bf16_f32 v51, v60, v61
	v_mul_f32_e32 v57, v46, v56
	v_lshl_add_u64 v[54:55], v[54:55], 0, v[116:117]
	v_exp_f32_e32 v57, v57
	global_store_dwordx4 v[54:55], v[50:53], off nt
	s_nop 1
	v_mul_f32_e32 v52, v38, v56
	v_exp_f32_e32 v53, v52
	v_mul_f32_e32 v52, v47, v56
	v_exp_f32_e32 v55, v52
	v_add_f32_e32 v51, 1.0, v57
	v_rcp_f32_e32 v52, v51
	v_add_f32_e32 v51, 1.0, v53
	v_rcp_f32_e32 v54, v51
	v_add_f32_e32 v51, 1.0, v55
	v_rcp_f32_e32 v53, v51
	v_mul_f32_e32 v51, v39, v56
	v_exp_f32_e32 v51, v51
	v_mul_f32_e32 v38, v48, v56
	v_mul_f32_e32 v50, v155, v155
	v_add_f32_e32 v46, 1.0, v51
	v_rcp_f32_e32 v55, v46
	v_exp_f32_e32 v46, v38
	v_mul_f32_e32 v38, v40, v56
	v_exp_f32_e32 v40, v38
	v_pk_mul_f32 v[34:35], v[34:35], v[50:51] op_sel_hi:[1,0]
	v_pk_mul_f32 v[44:45], v[44:45], v[50:51] op_sel_hi:[1,0]
	v_pk_mul_f32 v[38:39], v[34:35], v[54:55]
	v_add_f32_e32 v35, 1.0, v40
	v_mul_f32_e32 v40, v49, v56
	v_add_f32_e32 v34, 1.0, v46
	v_exp_f32_e32 v46, v40
	v_mul_f32_e32 v40, v41, v56
	v_exp_f32_e32 v41, v40
	v_rcp_f32_e32 v40, v35
	v_add_f32_e32 v35, 1.0, v46
	v_rcp_f32_e32 v34, v34
	v_rcp_f32_e32 v35, v35
	v_add_f32_e32 v41, 1.0, v41
	v_rcp_f32_e32 v41, v41
	v_pk_mul_f32 v[42:43], v[42:43], v[50:51] op_sel_hi:[1,0]
	v_pk_mul_f32 v[44:45], v[44:45], v[34:35]
	v_pk_mul_f32 v[34:35], v[36:37], v[50:51] op_sel_hi:[1,0]
	v_pk_mul_f32 v[42:43], v[42:43], v[52:53]
	v_pk_mul_f32 v[40:41], v[34:35], v[40:41]
	v_cvt_pk_bf16_f32 v36, v38, v39
	v_cvt_pk_bf16_f32 v37, v40, v41
	v_mad_i64_i32 v[38:39], s[4:5], v150, s61, v[114:115]
	v_mul_f32_e32 v40, 0xbfb8aa3b, v149
	v_cvt_pk_bf16_f32 v34, v42, v43
	v_cvt_pk_bf16_f32 v35, v44, v45
	v_mul_f32_e32 v41, v30, v40
	v_lshl_add_u64 v[38:39], v[38:39], 0, v[116:117]
	v_exp_f32_e32 v41, v41
	global_store_dwordx4 v[38:39], v[34:37], off nt
	s_nop 1
	v_mul_f32_e32 v36, v22, v40
	v_exp_f32_e32 v37, v36
	v_mul_f32_e32 v36, v31, v40
	v_exp_f32_e32 v39, v36
	v_add_f32_e32 v35, 1.0, v41
	v_rcp_f32_e32 v36, v35
	v_add_f32_e32 v35, 1.0, v37
	v_rcp_f32_e32 v38, v35
	v_add_f32_e32 v35, 1.0, v39
	v_rcp_f32_e32 v37, v35
	v_mul_f32_e32 v35, v23, v40
	v_exp_f32_e32 v35, v35
	v_mul_f32_e32 v22, v32, v40
	v_mul_f32_e32 v34, v149, v149
	v_add_f32_e32 v30, 1.0, v35
	v_rcp_f32_e32 v39, v30
	v_exp_f32_e32 v30, v22
	v_mul_f32_e32 v22, v24, v40
	v_exp_f32_e32 v24, v22
	v_pk_mul_f32 v[18:19], v[18:19], v[34:35] op_sel_hi:[1,0]
	v_pk_mul_f32 v[28:29], v[28:29], v[34:35] op_sel_hi:[1,0]
	v_pk_mul_f32 v[22:23], v[18:19], v[38:39]
	v_add_f32_e32 v19, 1.0, v24
	v_mul_f32_e32 v24, v33, v40
	v_add_f32_e32 v18, 1.0, v30
	v_exp_f32_e32 v30, v24
	v_mul_f32_e32 v24, v25, v40
	v_exp_f32_e32 v25, v24
	v_rcp_f32_e32 v24, v19
	v_add_f32_e32 v19, 1.0, v30
	v_rcp_f32_e32 v18, v18
	v_rcp_f32_e32 v19, v19
	v_add_f32_e32 v25, 1.0, v25
	v_rcp_f32_e32 v25, v25
	v_pk_mul_f32 v[26:27], v[26:27], v[34:35] op_sel_hi:[1,0]
	v_pk_mul_f32 v[28:29], v[28:29], v[18:19]
	v_pk_mul_f32 v[18:19], v[20:21], v[34:35] op_sel_hi:[1,0]
	v_pk_mul_f32 v[26:27], v[26:27], v[36:37]
	v_pk_mul_f32 v[24:25], v[18:19], v[24:25]
	v_cvt_pk_bf16_f32 v20, v22, v23
	v_cvt_pk_bf16_f32 v21, v24, v25
	v_mad_i64_i32 v[22:23], s[4:5], v148, s61, v[114:115]
	v_mul_f32_e32 v24, 0xbfb8aa3b, v147
	v_cvt_pk_bf16_f32 v18, v26, v27
	v_cvt_pk_bf16_f32 v19, v28, v29
	v_mul_f32_e32 v25, v14, v24
	v_lshl_add_u64 v[22:23], v[22:23], 0, v[116:117]
	v_exp_f32_e32 v25, v25
	global_store_dwordx4 v[22:23], v[18:21], off nt
	s_nop 1
	v_mul_f32_e32 v20, v6, v24
	v_exp_f32_e32 v21, v20
	v_mul_f32_e32 v20, v15, v24
	v_exp_f32_e32 v23, v20
	v_add_f32_e32 v19, 1.0, v25
	v_rcp_f32_e32 v20, v19
	v_add_f32_e32 v19, 1.0, v21
	v_rcp_f32_e32 v22, v19
	v_add_f32_e32 v19, 1.0, v23
	v_rcp_f32_e32 v21, v19
	v_mul_f32_e32 v19, v7, v24
	v_exp_f32_e32 v19, v19
	v_mul_f32_e32 v6, v16, v24
	v_mul_f32_e32 v18, v147, v147
	v_add_f32_e32 v14, 1.0, v19
	v_rcp_f32_e32 v23, v14
	v_exp_f32_e32 v14, v6
	v_mul_f32_e32 v6, v8, v24
	v_exp_f32_e32 v8, v6
	v_pk_mul_f32 v[2:3], v[2:3], v[18:19] op_sel_hi:[1,0]
	v_pk_mul_f32 v[12:13], v[12:13], v[18:19] op_sel_hi:[1,0]
	v_pk_mul_f32 v[6:7], v[2:3], v[22:23]
	v_add_f32_e32 v3, 1.0, v8
	v_mul_f32_e32 v8, v17, v24
	v_add_f32_e32 v2, 1.0, v14
	v_exp_f32_e32 v14, v8
	v_mul_f32_e32 v8, v9, v24
	v_exp_f32_e32 v9, v8
	v_rcp_f32_e32 v8, v3
	v_add_f32_e32 v3, 1.0, v14
	v_rcp_f32_e32 v2, v2
	v_rcp_f32_e32 v3, v3
	v_add_f32_e32 v9, 1.0, v9
	v_rcp_f32_e32 v9, v9
	v_pk_mul_f32 v[10:11], v[10:11], v[18:19] op_sel_hi:[1,0]
	v_pk_mul_f32 v[12:13], v[12:13], v[2:3]
	v_pk_mul_f32 v[2:3], v[4:5], v[18:19] op_sel_hi:[1,0]
	v_pk_mul_f32 v[10:11], v[10:11], v[20:21]
	v_pk_mul_f32 v[8:9], v[2:3], v[8:9]
	v_cvt_pk_bf16_f32 v4, v6, v7
	v_mad_i64_i32 v[6:7], s[4:5], v146, s61, v[114:115]
	v_cvt_pk_bf16_f32 v2, v10, v11
	v_cvt_pk_bf16_f32 v3, v12, v13
	v_cvt_pk_bf16_f32 v5, v8, v9
	v_lshl_add_u64 v[6:7], v[6:7], 0, v[116:117]
	global_store_dwordx4 v[6:7], v[2:5], off nt
	s_cbranch_vccnz .LBB0_1424
	s_andn2_b64 vcc, exec, s[26:27]
	s_cbranch_vccnz .LBB0_1423
	s_barrier
	s_branch .LBB0_1423
